# grid barrier: XCD leader issues its post-release invalidate and local-generation bump without first waiting for the release-word atomic's ack
# baseline (speedup 1.0000x reference)
; __device__ __forceinline__ unsigned xb_ld(unsigned* p)              { return __hip_atomic_load(p, __ATOMIC_RELAXED, __HIP_MEMORY_SCOPE_AGENT); }
; __device__ __forceinline__ unsigned xb_add(unsigned* p, unsigned v) { return __hip_atomic_fetch_add(p, v, __ATOMIC_RELAXED, __HIP_MEMORY_SCOPE_AGENT); }
; #define XB_SPIN(cond, bar) do { unsigned _sp = 0; while (cond) { __builtin_amdgcn_s_sleep(1); \
;     if ((++_sp & 255u) == 0u) { if (xb_ld(&(bar)[XB_TMO])) break; if (_sp > XB_SPIN_CAP) { atomicAdd(&(bar)[XB_TMO], 1u); break; } } } } while (0)
; __device__ __forceinline__ void xcd_barrier(const XcdBarrier& b) {
;     ...
;             else XB_SPIN(xb_ld(&bar[XB_TOPGEN]) == tg, bar);
;             __builtin_amdgcn_fence(__ATOMIC_ACQUIRE, "agent");
;             xb_add(&bar[XB_XGEN(b.x)], 1u);
;             asm volatile("s_waitcnt vmcnt(0)" ::: "memory");
.LBB0_284:
	s_or_b64 exec, exec, s[6:7]
	s_mov_b64 s[6:7], exec
	v_mbcnt_lo_u32_b32 v0, s6, 0
	v_mbcnt_hi_u32_b32 v0, s7, v0
	v_cmp_eq_u32_e32 vcc, 0, v0
	s_nop 0
	buffer_inv sc1
	s_and_saveexec_b64 s[8:9], vcc
	s_cbranch_execz .LBB0_286
	s_bcnt1_i32_b64 s6, s[6:7]
	v_mov_b32_e32 v0, s6
	v_readlane_b32 s6, v253, 9
	v_readlane_b32 s7, v253, 10
	s_nop 4
	global_atomic_add v1, v0, s[6:7]

; __device__ __forceinline__ unsigned xb_ld(unsigned* p)              { return __hip_atomic_load(p, __ATOMIC_RELAXED, __HIP_MEMORY_SCOPE_AGENT); }
; __device__ __forceinline__ unsigned xb_add(unsigned* p, unsigned v) { return __hip_atomic_fetch_add(p, v, __ATOMIC_RELAXED, __HIP_MEMORY_SCOPE_AGENT); }
; #define XB_SPIN(cond, bar) do { unsigned _sp = 0; while (cond) { __builtin_amdgcn_s_sleep(1); \
;     if ((++_sp & 255u) == 0u) { if (xb_ld(&(bar)[XB_TMO])) break; if (_sp > XB_SPIN_CAP) { atomicAdd(&(bar)[XB_TMO], 1u); break; } } } } while (0)
; __device__ __forceinline__ void xcd_barrier(const XcdBarrier& b) {
;     ...
;             else XB_SPIN(xb_ld(&bar[XB_TOPGEN]) == tg, bar);
;             __builtin_amdgcn_fence(__ATOMIC_ACQUIRE, "agent");
;             xb_add(&bar[XB_XGEN(b.x)], 1u);
;             asm volatile("s_waitcnt vmcnt(0)" ::: "memory");
.LBB0_1624:
	s_or_b64 exec, exec, s[8:9]
	s_mov_b64 s[8:9], exec
	v_mbcnt_lo_u32_b32 v0, s8, 0
	v_mbcnt_hi_u32_b32 v0, s9, v0
	v_cmp_eq_u32_e32 vcc, 0, v0
	s_nop 0
	buffer_inv sc1
	s_and_saveexec_b64 s[10:11], vcc
	s_cbranch_execz .LBB0_1626
	s_bcnt1_i32_b64 s8, s[8:9]
	v_mov_b32_e32 v0, s8
	v_readlane_b32 s8, v253, 9
	v_readlane_b32 s9, v253, 10
	s_nop 4
	global_atomic_add v1, v0, s[8:9]

; __device__ __forceinline__ unsigned xb_ld(unsigned* p)              { return __hip_atomic_load(p, __ATOMIC_RELAXED, __HIP_MEMORY_SCOPE_AGENT); }
; __device__ __forceinline__ unsigned xb_add(unsigned* p, unsigned v) { return __hip_atomic_fetch_add(p, v, __ATOMIC_RELAXED, __HIP_MEMORY_SCOPE_AGENT); }
; #define XB_SPIN(cond, bar) do { unsigned _sp = 0; while (cond) { __builtin_amdgcn_s_sleep(1); \
;     if ((++_sp & 255u) == 0u) { if (xb_ld(&(bar)[XB_TMO])) break; if (_sp > XB_SPIN_CAP) { atomicAdd(&(bar)[XB_TMO], 1u); break; } } } } while (0)
; __device__ __forceinline__ void xcd_barrier(const XcdBarrier& b) {
;     ...
;             else XB_SPIN(xb_ld(&bar[XB_TOPGEN]) == tg, bar);
;             __builtin_amdgcn_fence(__ATOMIC_ACQUIRE, "agent");
;             xb_add(&bar[XB_XGEN(b.x)], 1u);
;             asm volatile("s_waitcnt vmcnt(0)" ::: "memory");
.LBB0_1845:
	s_or_b64 exec, exec, s[6:7]
	s_mov_b64 s[6:7], exec
	v_mbcnt_lo_u32_b32 v0, s6, 0
	v_mbcnt_hi_u32_b32 v0, s7, v0
	v_cmp_eq_u32_e32 vcc, 0, v0
	s_nop 0
	buffer_inv sc1
	s_and_saveexec_b64 s[8:9], vcc
	s_cbranch_execnz .LBB0_1846
	s_getpc_b64 s[98:99]
